# conv3+SiLU strips: last row group of a strip re-reads its own last row instead of prefetching 4 rows past the strip (Z over-read removed)
# speedup vs baseline: 1.0016x; 1.0016x over previous
.Lgrp_cz0:
	s_cmp_eq_u32 s22, 1
	s_cselect_b32 s26, 0, 0xac00
	s_cselect_b32 s27, 0xac00, 0
	v_and_b32_e32 v175, 0xff, v171
	v_cmp_ne_u32_e64 s[24:25], 0, v175
	v_add_u32_e32 v171, 1, v171
	s_nop 3
	v_cndmask_b32_e64 v98, 0, v98, s[24:25]
	v_cndmask_b32_e64 v99, 0, v99, s[24:25]
	v_cndmask_b32_e64 v100, 0, v100, s[24:25]
	v_cndmask_b32_e64 v101, 0, v101, s[24:25]
	v_cndmask_b32_e64 v102, 0, v102, s[24:25]
	v_cndmask_b32_e64 v103, 0, v103, s[24:25]
	v_cndmask_b32_e64 v104, 0, v104, s[24:25]
	v_cndmask_b32_e64 v105, 0, v105, s[24:25]
	v_cndmask_b32_e64 v106, 0, v106, s[24:25]
	v_cndmask_b32_e64 v107, 0, v107, s[24:25]
	v_cndmask_b32_e64 v108, 0, v108, s[24:25]
	v_cndmask_b32_e64 v109, 0, v109, s[24:25]
	v_cndmask_b32_e64 v110, 0, v110, s[24:25]
	v_cndmask_b32_e64 v111, 0, v111, s[24:25]
	v_cndmask_b32_e64 v112, 0, v112, s[24:25]
	v_cndmask_b32_e64 v113, 0, v113, s[24:25]
	v_cndmask_b32_e64 v114, 0, v114, s[24:25]
	v_cndmask_b32_e64 v115, 0, v115, s[24:25]
	v_cndmask_b32_e64 v116, 0, v116, s[24:25]
	v_cndmask_b32_e64 v117, 0, v117, s[24:25]
	v_cndmask_b32_e64 v118, 0, v118, s[24:25]
	v_cndmask_b32_e64 v119, 0, v119, s[24:25]
	v_cndmask_b32_e64 v120, 0, v120, s[24:25]
	v_cndmask_b32_e64 v121, 0, v121, s[24:25]
	v_cndmask_b32_e64 v122, 0, v122, s[24:25]
	v_cndmask_b32_e64 v123, 0, v123, s[24:25]
	v_cndmask_b32_e64 v124, 0, v124, s[24:25]
	v_cndmask_b32_e64 v125, 0, v125, s[24:25]
	v_cndmask_b32_e64 v126, 0, v126, s[24:25]
	v_cndmask_b32_e64 v127, 0, v127, s[24:25]
	v_cndmask_b32_e64 v128, 0, v128, s[24:25]
	v_cndmask_b32_e64 v129, 0, v129, s[24:25]
	s_waitcnt vmcnt(10)
	v_lshlrev_b32_e32 v130, 16, v66
	v_and_b32_e32 v131, 0xffff0000, v66
	v_lshlrev_b32_e32 v132, 16, v67
	v_and_b32_e32 v133, 0xffff0000, v67
	v_lshlrev_b32_e32 v134, 16, v68
	v_and_b32_e32 v135, 0xffff0000, v68
	v_lshlrev_b32_e32 v136, 16, v69
	v_and_b32_e32 v137, 0xffff0000, v69
	v_lshlrev_b32_e32 v138, 16, v70
	v_and_b32_e32 v139, 0xffff0000, v70
	v_lshlrev_b32_e32 v140, 16, v71
	v_and_b32_e32 v141, 0xffff0000, v71
	v_lshlrev_b32_e32 v142, 16, v72
	v_and_b32_e32 v143, 0xffff0000, v72
	v_lshlrev_b32_e32 v144, 16, v73
	v_and_b32_e32 v145, 0xffff0000, v73
	global_load_dwordx4 v[66:69], v172, s[16:17] nt
	global_load_dwordx4 v[70:73], v172, s[18:19] nt
	v_add_u32_e32 v172, 0xac00, v172
	v_pk_fma_f32 v[146:147], v[2:3], v[98:99], v[50:51]
	v_pk_fma_f32 v[148:149], v[4:5], v[100:101], v[52:53]
	v_pk_fma_f32 v[150:151], v[6:7], v[102:103], v[54:55]
	v_pk_fma_f32 v[152:153], v[8:9], v[104:105], v[56:57]
	v_pk_fma_f32 v[154:155], v[26:27], v[106:107], v[58:59]
	v_pk_fma_f32 v[156:157], v[28:29], v[108:109], v[60:61]
	v_pk_fma_f32 v[158:159], v[30:31], v[110:111], v[62:63]
	v_pk_fma_f32 v[160:161], v[32:33], v[112:113], v[64:65]
	v_pk_fma_f32 v[146:147], v[10:11], v[114:115], v[146:147]
	v_pk_fma_f32 v[148:149], v[12:13], v[116:117], v[148:149]
	v_pk_fma_f32 v[150:151], v[14:15], v[118:119], v[150:151]
	v_pk_fma_f32 v[152:153], v[16:17], v[120:121], v[152:153]
	v_pk_fma_f32 v[154:155], v[34:35], v[122:123], v[154:155]
	v_pk_fma_f32 v[156:157], v[36:37], v[124:125], v[156:157]
	v_pk_fma_f32 v[158:159], v[38:39], v[126:127], v[158:159]
	v_pk_fma_f32 v[160:161], v[40:41], v[128:129], v[160:161]
	v_pk_fma_f32 v[146:147], v[18:19], v[130:131], v[146:147]
	v_pk_fma_f32 v[148:149], v[20:21], v[132:133], v[148:149]
	v_pk_fma_f32 v[150:151], v[22:23], v[134:135], v[150:151]
	v_pk_fma_f32 v[152:153], v[24:25], v[136:137], v[152:153]
	v_pk_fma_f32 v[154:155], v[42:43], v[138:139], v[154:155]
	v_pk_fma_f32 v[156:157], v[44:45], v[140:141], v[156:157]
	v_pk_fma_f32 v[158:159], v[46:47], v[142:143], v[158:159]
	v_pk_fma_f32 v[160:161], v[48:49], v[144:145], v[160:161]
	v_mul_f32_e32 v162, 0xbfb8aa3b, v146
	v_mul_f32_e32 v163, 0xbfb8aa3b, v147
	v_mul_f32_e32 v164, 0xbfb8aa3b, v148
	v_mul_f32_e32 v165, 0xbfb8aa3b, v149
	v_mul_f32_e32 v166, 0xbfb8aa3b, v150
	v_mul_f32_e32 v167, 0xbfb8aa3b, v151
	v_mul_f32_e32 v168, 0xbfb8aa3b, v152
	v_mul_f32_e32 v169, 0xbfb8aa3b, v153
	v_exp_f32_e32 v162, v162
	v_exp_f32_e32 v163, v163
	v_exp_f32_e32 v164, v164
	v_exp_f32_e32 v165, v165
	v_exp_f32_e32 v166, v166
	v_exp_f32_e32 v167, v167
	v_exp_f32_e32 v168, v168
	v_exp_f32_e32 v169, v169
	v_add_f32_e32 v162, 1.0, v162
	v_add_f32_e32 v163, 1.0, v163
	v_add_f32_e32 v164, 1.0, v164
	v_add_f32_e32 v165, 1.0, v165
	v_add_f32_e32 v166, 1.0, v166
	v_add_f32_e32 v167, 1.0, v167
	v_add_f32_e32 v168, 1.0, v168
	v_add_f32_e32 v169, 1.0, v169
	v_rcp_f32_e32 v162, v162
	v_rcp_f32_e32 v163, v163
	v_rcp_f32_e32 v164, v164
	v_rcp_f32_e32 v165, v165
	v_rcp_f32_e32 v166, v166
	v_rcp_f32_e32 v167, v167
	v_rcp_f32_e32 v168, v168
	v_rcp_f32_e32 v169, v169
	s_nop 0
	v_pk_mul_f32 v[146:147], v[146:147], v[162:163]
	v_pk_mul_f32 v[148:149], v[148:149], v[164:165]
	v_pk_mul_f32 v[150:151], v[150:151], v[166:167]
	v_pk_mul_f32 v[152:153], v[152:153], v[168:169]
	v_pk_mul_f32 v[146:147], v[154:155], v[146:147]
	v_pk_mul_f32 v[148:149], v[156:157], v[148:149]
	v_pk_mul_f32 v[150:151], v[158:159], v[150:151]
	v_pk_mul_f32 v[152:153], v[160:161], v[152:153]
	v_cvt_pk_bf16_f32 v162, v146, v147
	v_cvt_pk_bf16_f32 v163, v148, v149
	v_cvt_pk_bf16_f32 v164, v150, v151
	v_cvt_pk_bf16_f32 v165, v152, v153
	global_store_dwordx4 v173, v[162:165], s[20:21]
	v_add_u32_e32 v173, 0x5600, v173
	s_waitcnt vmcnt(10)
	v_lshlrev_b32_e32 v98, 16, v74
	v_and_b32_e32 v99, 0xffff0000, v74
	v_lshlrev_b32_e32 v100, 16, v75
	v_and_b32_e32 v101, 0xffff0000, v75
	v_lshlrev_b32_e32 v102, 16, v76
	v_and_b32_e32 v103, 0xffff0000, v76
	v_lshlrev_b32_e32 v104, 16, v77
	v_and_b32_e32 v105, 0xffff0000, v77
	v_lshlrev_b32_e32 v106, 16, v78
	v_and_b32_e32 v107, 0xffff0000, v78
	v_lshlrev_b32_e32 v108, 16, v79
	v_and_b32_e32 v109, 0xffff0000, v79
	v_lshlrev_b32_e32 v110, 16, v80
	v_and_b32_e32 v111, 0xffff0000, v80
	v_lshlrev_b32_e32 v112, 16, v81
	v_and_b32_e32 v113, 0xffff0000, v81
	global_load_dwordx4 v[74:77], v172, s[16:17] nt
	global_load_dwordx4 v[78:81], v172, s[18:19] nt
	v_add_u32_e32 v172, 0xac00, v172
	v_pk_fma_f32 v[146:147], v[2:3], v[114:115], v[50:51]
	v_pk_fma_f32 v[148:149], v[4:5], v[116:117], v[52:53]
	v_pk_fma_f32 v[150:151], v[6:7], v[118:119], v[54:55]
	v_pk_fma_f32 v[152:153], v[8:9], v[120:121], v[56:57]
	v_pk_fma_f32 v[154:155], v[26:27], v[122:123], v[58:59]
	v_pk_fma_f32 v[156:157], v[28:29], v[124:125], v[60:61]
	v_pk_fma_f32 v[158:159], v[30:31], v[126:127], v[62:63]
	v_pk_fma_f32 v[160:161], v[32:33], v[128:129], v[64:65]
	v_pk_fma_f32 v[146:147], v[10:11], v[130:131], v[146:147]
	v_pk_fma_f32 v[148:149], v[12:13], v[132:133], v[148:149]
	v_pk_fma_f32 v[150:151], v[14:15], v[134:135], v[150:151]
	v_pk_fma_f32 v[152:153], v[16:17], v[136:137], v[152:153]
	v_pk_fma_f32 v[154:155], v[34:35], v[138:139], v[154:155]
	v_pk_fma_f32 v[156:157], v[36:37], v[140:141], v[156:157]
	v_pk_fma_f32 v[158:159], v[38:39], v[142:143], v[158:159]
	v_pk_fma_f32 v[160:161], v[40:41], v[144:145], v[160:161]
	v_pk_fma_f32 v[146:147], v[18:19], v[98:99], v[146:147]
	v_pk_fma_f32 v[148:149], v[20:21], v[100:101], v[148:149]
	v_pk_fma_f32 v[150:151], v[22:23], v[102:103], v[150:151]
	v_pk_fma_f32 v[152:153], v[24:25], v[104:105], v[152:153]
	v_pk_fma_f32 v[154:155], v[42:43], v[106:107], v[154:155]
	v_pk_fma_f32 v[156:157], v[44:45], v[108:109], v[156:157]
	v_pk_fma_f32 v[158:159], v[46:47], v[110:111], v[158:159]
	v_pk_fma_f32 v[160:161], v[48:49], v[112:113], v[160:161]
	v_mul_f32_e32 v162, 0xbfb8aa3b, v146
	v_mul_f32_e32 v163, 0xbfb8aa3b, v147
	v_mul_f32_e32 v164, 0xbfb8aa3b, v148
	v_mul_f32_e32 v165, 0xbfb8aa3b, v149
	v_mul_f32_e32 v166, 0xbfb8aa3b, v150
	v_mul_f32_e32 v167, 0xbfb8aa3b, v151
	v_mul_f32_e32 v168, 0xbfb8aa3b, v152
	v_mul_f32_e32 v169, 0xbfb8aa3b, v153
	v_exp_f32_e32 v162, v162
	v_exp_f32_e32 v163, v163
	v_exp_f32_e32 v164, v164
	v_exp_f32_e32 v165, v165
	v_exp_f32_e32 v166, v166
	v_exp_f32_e32 v167, v167
	v_exp_f32_e32 v168, v168
	v_exp_f32_e32 v169, v169
	v_add_f32_e32 v162, 1.0, v162
	v_add_f32_e32 v163, 1.0, v163
	v_add_f32_e32 v164, 1.0, v164
	v_add_f32_e32 v165, 1.0, v165
	v_add_f32_e32 v166, 1.0, v166
	v_add_f32_e32 v167, 1.0, v167
	v_add_f32_e32 v168, 1.0, v168
	v_add_f32_e32 v169, 1.0, v169
	v_rcp_f32_e32 v162, v162
	v_rcp_f32_e32 v163, v163
	v_rcp_f32_e32 v164, v164
	v_rcp_f32_e32 v165, v165
	v_rcp_f32_e32 v166, v166
	v_rcp_f32_e32 v167, v167
	v_rcp_f32_e32 v168, v168
	v_rcp_f32_e32 v169, v169
	s_nop 0
	v_pk_mul_f32 v[146:147], v[146:147], v[162:163]
	v_pk_mul_f32 v[148:149], v[148:149], v[164:165]
	v_pk_mul_f32 v[150:151], v[150:151], v[166:167]
	v_pk_mul_f32 v[152:153], v[152:153], v[168:169]
	v_pk_mul_f32 v[146:147], v[154:155], v[146:147]
	v_pk_mul_f32 v[148:149], v[156:157], v[148:149]
	v_pk_mul_f32 v[150:151], v[158:159], v[150:151]
	v_pk_mul_f32 v[152:153], v[160:161], v[152:153]
	v_cvt_pk_bf16_f32 v162, v146, v147
	v_cvt_pk_bf16_f32 v163, v148, v149
	v_cvt_pk_bf16_f32 v164, v150, v151
	v_cvt_pk_bf16_f32 v165, v152, v153
	global_store_dwordx4 v173, v[162:165], s[20:21]
	v_add_u32_e32 v173, 0x5600, v173
	s_waitcnt vmcnt(10)
	v_lshlrev_b32_e32 v114, 16, v82
	v_and_b32_e32 v115, 0xffff0000, v82
	v_lshlrev_b32_e32 v116, 16, v83
	v_and_b32_e32 v117, 0xffff0000, v83
	v_lshlrev_b32_e32 v118, 16, v84
	v_and_b32_e32 v119, 0xffff0000, v84
	v_lshlrev_b32_e32 v120, 16, v85
	v_and_b32_e32 v121, 0xffff0000, v85
	v_lshlrev_b32_e32 v122, 16, v86
	v_and_b32_e32 v123, 0xffff0000, v86
	v_lshlrev_b32_e32 v124, 16, v87
	v_and_b32_e32 v125, 0xffff0000, v87
	v_lshlrev_b32_e32 v126, 16, v88
	v_and_b32_e32 v127, 0xffff0000, v88
	v_lshlrev_b32_e32 v128, 16, v89
	v_and_b32_e32 v129, 0xffff0000, v89
	global_load_dwordx4 v[82:85], v172, s[16:17] nt
	global_load_dwordx4 v[86:89], v172, s[18:19] nt
	v_add_u32_e32 v172, 0xac00, v172
	v_pk_fma_f32 v[146:147], v[2:3], v[130:131], v[50:51]
	v_pk_fma_f32 v[148:149], v[4:5], v[132:133], v[52:53]
	v_pk_fma_f32 v[150:151], v[6:7], v[134:135], v[54:55]
	v_pk_fma_f32 v[152:153], v[8:9], v[136:137], v[56:57]
	v_pk_fma_f32 v[154:155], v[26:27], v[138:139], v[58:59]
	v_pk_fma_f32 v[156:157], v[28:29], v[140:141], v[60:61]
	v_pk_fma_f32 v[158:159], v[30:31], v[142:143], v[62:63]
	v_pk_fma_f32 v[160:161], v[32:33], v[144:145], v[64:65]
	v_pk_fma_f32 v[146:147], v[10:11], v[98:99], v[146:147]
	v_pk_fma_f32 v[148:149], v[12:13], v[100:101], v[148:149]
	v_pk_fma_f32 v[150:151], v[14:15], v[102:103], v[150:151]
	v_pk_fma_f32 v[152:153], v[16:17], v[104:105], v[152:153]
	v_pk_fma_f32 v[154:155], v[34:35], v[106:107], v[154:155]
	v_pk_fma_f32 v[156:157], v[36:37], v[108:109], v[156:157]
	v_pk_fma_f32 v[158:159], v[38:39], v[110:111], v[158:159]
	v_pk_fma_f32 v[160:161], v[40:41], v[112:113], v[160:161]
	v_pk_fma_f32 v[146:147], v[18:19], v[114:115], v[146:147]
	v_pk_fma_f32 v[148:149], v[20:21], v[116:117], v[148:149]
	v_pk_fma_f32 v[150:151], v[22:23], v[118:119], v[150:151]
	v_pk_fma_f32 v[152:153], v[24:25], v[120:121], v[152:153]
	v_pk_fma_f32 v[154:155], v[42:43], v[122:123], v[154:155]
	v_pk_fma_f32 v[156:157], v[44:45], v[124:125], v[156:157]
	v_pk_fma_f32 v[158:159], v[46:47], v[126:127], v[158:159]
	v_pk_fma_f32 v[160:161], v[48:49], v[128:129], v[160:161]
	v_mul_f32_e32 v162, 0xbfb8aa3b, v146
	v_mul_f32_e32 v163, 0xbfb8aa3b, v147
	v_mul_f32_e32 v164, 0xbfb8aa3b, v148
	v_mul_f32_e32 v165, 0xbfb8aa3b, v149
	v_mul_f32_e32 v166, 0xbfb8aa3b, v150
	v_mul_f32_e32 v167, 0xbfb8aa3b, v151
	v_mul_f32_e32 v168, 0xbfb8aa3b, v152
	v_mul_f32_e32 v169, 0xbfb8aa3b, v153
	v_exp_f32_e32 v162, v162
	v_exp_f32_e32 v163, v163
	v_exp_f32_e32 v164, v164
	v_exp_f32_e32 v165, v165
	v_exp_f32_e32 v166, v166
	v_exp_f32_e32 v167, v167
	v_exp_f32_e32 v168, v168
	v_exp_f32_e32 v169, v169
	v_add_f32_e32 v162, 1.0, v162
	v_add_f32_e32 v163, 1.0, v163
	v_add_f32_e32 v164, 1.0, v164
	v_add_f32_e32 v165, 1.0, v165
	v_add_f32_e32 v166, 1.0, v166
	v_add_f32_e32 v167, 1.0, v167
	v_add_f32_e32 v168, 1.0, v168
	v_add_f32_e32 v169, 1.0, v169
	v_rcp_f32_e32 v162, v162
	v_rcp_f32_e32 v163, v163
	v_rcp_f32_e32 v164, v164
	v_rcp_f32_e32 v165, v165
	v_rcp_f32_e32 v166, v166
	v_rcp_f32_e32 v167, v167
	v_rcp_f32_e32 v168, v168
	v_rcp_f32_e32 v169, v169
	s_nop 0
	v_pk_mul_f32 v[146:147], v[146:147], v[162:163]
	v_pk_mul_f32 v[148:149], v[148:149], v[164:165]
	v_pk_mul_f32 v[150:151], v[150:151], v[166:167]
	v_pk_mul_f32 v[152:153], v[152:153], v[168:169]
	v_pk_mul_f32 v[146:147], v[154:155], v[146:147]
	v_pk_mul_f32 v[148:149], v[156:157], v[148:149]
	v_pk_mul_f32 v[150:151], v[158:159], v[150:151]
	v_pk_mul_f32 v[152:153], v[160:161], v[152:153]
	v_cvt_pk_bf16_f32 v162, v146, v147
	v_cvt_pk_bf16_f32 v163, v148, v149
	v_cvt_pk_bf16_f32 v164, v150, v151
	v_cvt_pk_bf16_f32 v165, v152, v153
	global_store_dwordx4 v173, v[162:165], s[20:21]
	v_add_u32_e32 v173, 0x5600, v173
	s_waitcnt vmcnt(10)
	v_lshlrev_b32_e32 v130, 16, v90
	v_and_b32_e32 v131, 0xffff0000, v90
	v_lshlrev_b32_e32 v132, 16, v91
	v_and_b32_e32 v133, 0xffff0000, v91
	v_lshlrev_b32_e32 v134, 16, v92
	v_and_b32_e32 v135, 0xffff0000, v92
	v_lshlrev_b32_e32 v136, 16, v93
	v_and_b32_e32 v137, 0xffff0000, v93
	v_lshlrev_b32_e32 v138, 16, v94
	v_and_b32_e32 v139, 0xffff0000, v94
	v_lshlrev_b32_e32 v140, 16, v95
	v_and_b32_e32 v141, 0xffff0000, v95
	v_lshlrev_b32_e32 v142, 16, v96
	v_and_b32_e32 v143, 0xffff0000, v96
	v_lshlrev_b32_e32 v144, 16, v97
	v_and_b32_e32 v145, 0xffff0000, v97
	global_load_dwordx4 v[90:93], v172, s[16:17] nt
	global_load_dwordx4 v[94:97], v172, s[18:19] nt
	v_add_u32_e32 v172, 0xac00, v172
	v_pk_fma_f32 v[146:147], v[2:3], v[98:99], v[50:51]
	v_pk_fma_f32 v[148:149], v[4:5], v[100:101], v[52:53]
	v_pk_fma_f32 v[150:151], v[6:7], v[102:103], v[54:55]
	v_pk_fma_f32 v[152:153], v[8:9], v[104:105], v[56:57]
	v_pk_fma_f32 v[154:155], v[26:27], v[106:107], v[58:59]
	v_pk_fma_f32 v[156:157], v[28:29], v[108:109], v[60:61]
	v_pk_fma_f32 v[158:159], v[30:31], v[110:111], v[62:63]
	v_pk_fma_f32 v[160:161], v[32:33], v[112:113], v[64:65]
	v_pk_fma_f32 v[146:147], v[10:11], v[114:115], v[146:147]
	v_pk_fma_f32 v[148:149], v[12:13], v[116:117], v[148:149]
	v_pk_fma_f32 v[150:151], v[14:15], v[118:119], v[150:151]
	v_pk_fma_f32 v[152:153], v[16:17], v[120:121], v[152:153]
	v_pk_fma_f32 v[154:155], v[34:35], v[122:123], v[154:155]
	v_pk_fma_f32 v[156:157], v[36:37], v[124:125], v[156:157]
	v_pk_fma_f32 v[158:159], v[38:39], v[126:127], v[158:159]
	v_pk_fma_f32 v[160:161], v[40:41], v[128:129], v[160:161]
	v_pk_fma_f32 v[146:147], v[18:19], v[130:131], v[146:147]
	v_pk_fma_f32 v[148:149], v[20:21], v[132:133], v[148:149]
	v_pk_fma_f32 v[150:151], v[22:23], v[134:135], v[150:151]
	v_pk_fma_f32 v[152:153], v[24:25], v[136:137], v[152:153]
	v_pk_fma_f32 v[154:155], v[42:43], v[138:139], v[154:155]
	v_pk_fma_f32 v[156:157], v[44:45], v[140:141], v[156:157]
	v_pk_fma_f32 v[158:159], v[46:47], v[142:143], v[158:159]
	v_pk_fma_f32 v[160:161], v[48:49], v[144:145], v[160:161]
	v_mul_f32_e32 v162, 0xbfb8aa3b, v146
	v_mul_f32_e32 v163, 0xbfb8aa3b, v147
	v_mul_f32_e32 v164, 0xbfb8aa3b, v148
	v_mul_f32_e32 v165, 0xbfb8aa3b, v149
	v_mul_f32_e32 v166, 0xbfb8aa3b, v150
	v_mul_f32_e32 v167, 0xbfb8aa3b, v151
	v_mul_f32_e32 v168, 0xbfb8aa3b, v152
	v_mul_f32_e32 v169, 0xbfb8aa3b, v153
	v_exp_f32_e32 v162, v162
	v_exp_f32_e32 v163, v163
	v_exp_f32_e32 v164, v164
	v_exp_f32_e32 v165, v165
	v_exp_f32_e32 v166, v166
	v_exp_f32_e32 v167, v167
	v_exp_f32_e32 v168, v168
	v_exp_f32_e32 v169, v169
	v_add_f32_e32 v162, 1.0, v162
	v_add_f32_e32 v163, 1.0, v163
	v_add_f32_e32 v164, 1.0, v164
	v_add_f32_e32 v165, 1.0, v165
	v_add_f32_e32 v166, 1.0, v166
	v_add_f32_e32 v167, 1.0, v167
	v_add_f32_e32 v168, 1.0, v168
	v_add_f32_e32 v169, 1.0, v169
	v_rcp_f32_e32 v162, v162
	v_rcp_f32_e32 v163, v163
	v_rcp_f32_e32 v164, v164
	v_rcp_f32_e32 v165, v165
	v_rcp_f32_e32 v166, v166
	v_rcp_f32_e32 v167, v167
	v_rcp_f32_e32 v168, v168
	v_rcp_f32_e32 v169, v169
	s_nop 0
	v_pk_mul_f32 v[146:147], v[146:147], v[162:163]
	v_pk_mul_f32 v[148:149], v[148:149], v[164:165]
	v_pk_mul_f32 v[150:151], v[150:151], v[166:167]
	v_pk_mul_f32 v[152:153], v[152:153], v[168:169]
	v_pk_mul_f32 v[146:147], v[154:155], v[146:147]
	v_pk_mul_f32 v[148:149], v[156:157], v[148:149]
	v_pk_mul_f32 v[150:151], v[158:159], v[150:151]
	v_pk_mul_f32 v[152:153], v[160:161], v[152:153]
	v_cvt_pk_bf16_f32 v162, v146, v147
	v_cvt_pk_bf16_f32 v163, v148, v149
	v_cvt_pk_bf16_f32 v164, v150, v151
	v_cvt_pk_bf16_f32 v165, v152, v153
	global_store_dwordx4 v173, v[162:165], s[20:21]
	v_add_u32_e32 v173, 0x5600, v173
	s_waitcnt vmcnt(10)
	v_lshlrev_b32_e32 v98, 16, v66
	v_and_b32_e32 v99, 0xffff0000, v66
	v_lshlrev_b32_e32 v100, 16, v67
	v_and_b32_e32 v101, 0xffff0000, v67
	v_lshlrev_b32_e32 v102, 16, v68
	v_and_b32_e32 v103, 0xffff0000, v68
	v_lshlrev_b32_e32 v104, 16, v69
	v_and_b32_e32 v105, 0xffff0000, v69
	v_lshlrev_b32_e32 v106, 16, v70
	v_and_b32_e32 v107, 0xffff0000, v70
	v_lshlrev_b32_e32 v108, 16, v71
	v_and_b32_e32 v109, 0xffff0000, v71
	v_lshlrev_b32_e32 v110, 16, v72
	v_and_b32_e32 v111, 0xffff0000, v72
	v_lshlrev_b32_e32 v112, 16, v73
	v_and_b32_e32 v113, 0xffff0000, v73
	v_subrev_u32_e32 v180, s27, v172
	global_load_dwordx4 v[66:69], v180, s[16:17] nt
	global_load_dwordx4 v[70:73], v180, s[18:19] nt
	v_add_u32_e32 v180, s26, v180
	v_pk_fma_f32 v[146:147], v[2:3], v[114:115], v[50:51]
	v_pk_fma_f32 v[148:149], v[4:5], v[116:117], v[52:53]
	v_pk_fma_f32 v[150:151], v[6:7], v[118:119], v[54:55]
	v_pk_fma_f32 v[152:153], v[8:9], v[120:121], v[56:57]
	v_pk_fma_f32 v[154:155], v[26:27], v[122:123], v[58:59]
	v_pk_fma_f32 v[156:157], v[28:29], v[124:125], v[60:61]
	v_pk_fma_f32 v[158:159], v[30:31], v[126:127], v[62:63]
	v_pk_fma_f32 v[160:161], v[32:33], v[128:129], v[64:65]
	v_pk_fma_f32 v[146:147], v[10:11], v[130:131], v[146:147]
	v_pk_fma_f32 v[148:149], v[12:13], v[132:133], v[148:149]
	v_pk_fma_f32 v[150:151], v[14:15], v[134:135], v[150:151]
	v_pk_fma_f32 v[152:153], v[16:17], v[136:137], v[152:153]
	v_pk_fma_f32 v[154:155], v[34:35], v[138:139], v[154:155]
	v_pk_fma_f32 v[156:157], v[36:37], v[140:141], v[156:157]
	v_pk_fma_f32 v[158:159], v[38:39], v[142:143], v[158:159]
	v_pk_fma_f32 v[160:161], v[40:41], v[144:145], v[160:161]
	v_pk_fma_f32 v[146:147], v[18:19], v[98:99], v[146:147]
	v_pk_fma_f32 v[148:149], v[20:21], v[100:101], v[148:149]
	v_pk_fma_f32 v[150:151], v[22:23], v[102:103], v[150:151]
	v_pk_fma_f32 v[152:153], v[24:25], v[104:105], v[152:153]
	v_pk_fma_f32 v[154:155], v[42:43], v[106:107], v[154:155]
	v_pk_fma_f32 v[156:157], v[44:45], v[108:109], v[156:157]
	v_pk_fma_f32 v[158:159], v[46:47], v[110:111], v[158:159]
	v_pk_fma_f32 v[160:161], v[48:49], v[112:113], v[160:161]
	v_mul_f32_e32 v162, 0xbfb8aa3b, v146
	v_mul_f32_e32 v163, 0xbfb8aa3b, v147
	v_mul_f32_e32 v164, 0xbfb8aa3b, v148
	v_mul_f32_e32 v165, 0xbfb8aa3b, v149
	v_mul_f32_e32 v166, 0xbfb8aa3b, v150
	v_mul_f32_e32 v167, 0xbfb8aa3b, v151
	v_mul_f32_e32 v168, 0xbfb8aa3b, v152
	v_mul_f32_e32 v169, 0xbfb8aa3b, v153
	v_exp_f32_e32 v162, v162
	v_exp_f32_e32 v163, v163
	v_exp_f32_e32 v164, v164
	v_exp_f32_e32 v165, v165
	v_exp_f32_e32 v166, v166
	v_exp_f32_e32 v167, v167
	v_exp_f32_e32 v168, v168
	v_exp_f32_e32 v169, v169
	v_add_f32_e32 v162, 1.0, v162
	v_add_f32_e32 v163, 1.0, v163
	v_add_f32_e32 v164, 1.0, v164
	v_add_f32_e32 v165, 1.0, v165
	v_add_f32_e32 v166, 1.0, v166
	v_add_f32_e32 v167, 1.0, v167
	v_add_f32_e32 v168, 1.0, v168
	v_add_f32_e32 v169, 1.0, v169
	v_rcp_f32_e32 v162, v162
	v_rcp_f32_e32 v163, v163
	v_rcp_f32_e32 v164, v164
	v_rcp_f32_e32 v165, v165
	v_rcp_f32_e32 v166, v166
	v_rcp_f32_e32 v167, v167
	v_rcp_f32_e32 v168, v168
	v_rcp_f32_e32 v169, v169
	s_nop 0
	v_pk_mul_f32 v[146:147], v[146:147], v[162:163]
	v_pk_mul_f32 v[148:149], v[148:149], v[164:165]
	v_pk_mul_f32 v[150:151], v[150:151], v[166:167]
	v_pk_mul_f32 v[152:153], v[152:153], v[168:169]
	v_pk_mul_f32 v[146:147], v[154:155], v[146:147]
	v_pk_mul_f32 v[148:149], v[156:157], v[148:149]
	v_pk_mul_f32 v[150:151], v[158:159], v[150:151]
	v_pk_mul_f32 v[152:153], v[160:161], v[152:153]
	v_cvt_pk_bf16_f32 v162, v146, v147
	v_cvt_pk_bf16_f32 v163, v148, v149
	v_cvt_pk_bf16_f32 v164, v150, v151
	v_cvt_pk_bf16_f32 v165, v152, v153
	global_store_dwordx4 v173, v[162:165], s[20:21]
	v_add_u32_e32 v173, 0x5600, v173
	s_waitcnt vmcnt(10)
	v_lshlrev_b32_e32 v114, 16, v74
	v_and_b32_e32 v115, 0xffff0000, v74
	v_lshlrev_b32_e32 v116, 16, v75
	v_and_b32_e32 v117, 0xffff0000, v75
	v_lshlrev_b32_e32 v118, 16, v76
	v_and_b32_e32 v119, 0xffff0000, v76
	v_lshlrev_b32_e32 v120, 16, v77
	v_and_b32_e32 v121, 0xffff0000, v77
	v_lshlrev_b32_e32 v122, 16, v78
	v_and_b32_e32 v123, 0xffff0000, v78
	v_lshlrev_b32_e32 v124, 16, v79
	v_and_b32_e32 v125, 0xffff0000, v79
	v_lshlrev_b32_e32 v126, 16, v80
	v_and_b32_e32 v127, 0xffff0000, v80
	v_lshlrev_b32_e32 v128, 16, v81
	v_and_b32_e32 v129, 0xffff0000, v81
	global_load_dwordx4 v[74:77], v180, s[16:17] nt
	global_load_dwordx4 v[78:81], v180, s[18:19] nt
	v_add_u32_e32 v180, s26, v180
	v_pk_fma_f32 v[146:147], v[2:3], v[130:131], v[50:51]
	v_pk_fma_f32 v[148:149], v[4:5], v[132:133], v[52:53]
	v_pk_fma_f32 v[150:151], v[6:7], v[134:135], v[54:55]
	v_pk_fma_f32 v[152:153], v[8:9], v[136:137], v[56:57]
	v_pk_fma_f32 v[154:155], v[26:27], v[138:139], v[58:59]
	v_pk_fma_f32 v[156:157], v[28:29], v[140:141], v[60:61]
	v_pk_fma_f32 v[158:159], v[30:31], v[142:143], v[62:63]
	v_pk_fma_f32 v[160:161], v[32:33], v[144:145], v[64:65]
	v_pk_fma_f32 v[146:147], v[10:11], v[98:99], v[146:147]
	v_pk_fma_f32 v[148:149], v[12:13], v[100:101], v[148:149]
	v_pk_fma_f32 v[150:151], v[14:15], v[102:103], v[150:151]
	v_pk_fma_f32 v[152:153], v[16:17], v[104:105], v[152:153]
	v_pk_fma_f32 v[154:155], v[34:35], v[106:107], v[154:155]
	v_pk_fma_f32 v[156:157], v[36:37], v[108:109], v[156:157]
	v_pk_fma_f32 v[158:159], v[38:39], v[110:111], v[158:159]
	v_pk_fma_f32 v[160:161], v[40:41], v[112:113], v[160:161]
	v_pk_fma_f32 v[146:147], v[18:19], v[114:115], v[146:147]
	v_pk_fma_f32 v[148:149], v[20:21], v[116:117], v[148:149]
	v_pk_fma_f32 v[150:151], v[22:23], v[118:119], v[150:151]
	v_pk_fma_f32 v[152:153], v[24:25], v[120:121], v[152:153]
	v_pk_fma_f32 v[154:155], v[42:43], v[122:123], v[154:155]
	v_pk_fma_f32 v[156:157], v[44:45], v[124:125], v[156:157]
	v_pk_fma_f32 v[158:159], v[46:47], v[126:127], v[158:159]
	v_pk_fma_f32 v[160:161], v[48:49], v[128:129], v[160:161]
	v_mul_f32_e32 v162, 0xbfb8aa3b, v146
	v_mul_f32_e32 v163, 0xbfb8aa3b, v147
	v_mul_f32_e32 v164, 0xbfb8aa3b, v148
	v_mul_f32_e32 v165, 0xbfb8aa3b, v149
	v_mul_f32_e32 v166, 0xbfb8aa3b, v150
	v_mul_f32_e32 v167, 0xbfb8aa3b, v151
	v_mul_f32_e32 v168, 0xbfb8aa3b, v152
	v_mul_f32_e32 v169, 0xbfb8aa3b, v153
	v_exp_f32_e32 v162, v162
	v_exp_f32_e32 v163, v163
	v_exp_f32_e32 v164, v164
	v_exp_f32_e32 v165, v165
	v_exp_f32_e32 v166, v166
	v_exp_f32_e32 v167, v167
	v_exp_f32_e32 v168, v168
	v_exp_f32_e32 v169, v169
	v_add_f32_e32 v162, 1.0, v162
	v_add_f32_e32 v163, 1.0, v163
	v_add_f32_e32 v164, 1.0, v164
	v_add_f32_e32 v165, 1.0, v165
	v_add_f32_e32 v166, 1.0, v166
	v_add_f32_e32 v167, 1.0, v167
	v_add_f32_e32 v168, 1.0, v168
	v_add_f32_e32 v169, 1.0, v169
	v_rcp_f32_e32 v162, v162
	v_rcp_f32_e32 v163, v163
	v_rcp_f32_e32 v164, v164
	v_rcp_f32_e32 v165, v165
	v_rcp_f32_e32 v166, v166
	v_rcp_f32_e32 v167, v167
	v_rcp_f32_e32 v168, v168
	v_rcp_f32_e32 v169, v169
	s_nop 0
	v_pk_mul_f32 v[146:147], v[146:147], v[162:163]
	v_pk_mul_f32 v[148:149], v[148:149], v[164:165]
	v_pk_mul_f32 v[150:151], v[150:151], v[166:167]
	v_pk_mul_f32 v[152:153], v[152:153], v[168:169]
	v_pk_mul_f32 v[146:147], v[154:155], v[146:147]
	v_pk_mul_f32 v[148:149], v[156:157], v[148:149]
	v_pk_mul_f32 v[150:151], v[158:159], v[150:151]
	v_pk_mul_f32 v[152:153], v[160:161], v[152:153]
	v_cvt_pk_bf16_f32 v162, v146, v147
	v_cvt_pk_bf16_f32 v163, v148, v149
	v_cvt_pk_bf16_f32 v164, v150, v151
	v_cvt_pk_bf16_f32 v165, v152, v153
	global_store_dwordx4 v173, v[162:165], s[20:21]
	v_add_u32_e32 v173, 0x5600, v173
	s_waitcnt vmcnt(10)
	v_lshlrev_b32_e32 v130, 16, v82
	v_and_b32_e32 v131, 0xffff0000, v82
	v_lshlrev_b32_e32 v132, 16, v83
	v_and_b32_e32 v133, 0xffff0000, v83
	v_lshlrev_b32_e32 v134, 16, v84
	v_and_b32_e32 v135, 0xffff0000, v84
	v_lshlrev_b32_e32 v136, 16, v85
	v_and_b32_e32 v137, 0xffff0000, v85
	v_lshlrev_b32_e32 v138, 16, v86
	v_and_b32_e32 v139, 0xffff0000, v86
	v_lshlrev_b32_e32 v140, 16, v87
	v_and_b32_e32 v141, 0xffff0000, v87
	v_lshlrev_b32_e32 v142, 16, v88
	v_and_b32_e32 v143, 0xffff0000, v88
	v_lshlrev_b32_e32 v144, 16, v89
	v_and_b32_e32 v145, 0xffff0000, v89
	global_load_dwordx4 v[82:85], v180, s[16:17] nt
	global_load_dwordx4 v[86:89], v180, s[18:19] nt
	v_add_u32_e32 v180, s26, v180
	v_pk_fma_f32 v[146:147], v[2:3], v[98:99], v[50:51]
	v_pk_fma_f32 v[148:149], v[4:5], v[100:101], v[52:53]
	v_pk_fma_f32 v[150:151], v[6:7], v[102:103], v[54:55]
	v_pk_fma_f32 v[152:153], v[8:9], v[104:105], v[56:57]
	v_pk_fma_f32 v[154:155], v[26:27], v[106:107], v[58:59]
	v_pk_fma_f32 v[156:157], v[28:29], v[108:109], v[60:61]
	v_pk_fma_f32 v[158:159], v[30:31], v[110:111], v[62:63]
	v_pk_fma_f32 v[160:161], v[32:33], v[112:113], v[64:65]
	v_pk_fma_f32 v[146:147], v[10:11], v[114:115], v[146:147]
	v_pk_fma_f32 v[148:149], v[12:13], v[116:117], v[148:149]
	v_pk_fma_f32 v[150:151], v[14:15], v[118:119], v[150:151]
	v_pk_fma_f32 v[152:153], v[16:17], v[120:121], v[152:153]
	v_pk_fma_f32 v[154:155], v[34:35], v[122:123], v[154:155]
	v_pk_fma_f32 v[156:157], v[36:37], v[124:125], v[156:157]
	v_pk_fma_f32 v[158:159], v[38:39], v[126:127], v[158:159]
	v_pk_fma_f32 v[160:161], v[40:41], v[128:129], v[160:161]
	v_pk_fma_f32 v[146:147], v[18:19], v[130:131], v[146:147]
	v_pk_fma_f32 v[148:149], v[20:21], v[132:133], v[148:149]
	v_pk_fma_f32 v[150:151], v[22:23], v[134:135], v[150:151]
	v_pk_fma_f32 v[152:153], v[24:25], v[136:137], v[152:153]
	v_pk_fma_f32 v[154:155], v[42:43], v[138:139], v[154:155]
	v_pk_fma_f32 v[156:157], v[44:45], v[140:141], v[156:157]
	v_pk_fma_f32 v[158:159], v[46:47], v[142:143], v[158:159]
	v_pk_fma_f32 v[160:161], v[48:49], v[144:145], v[160:161]
	v_mul_f32_e32 v162, 0xbfb8aa3b, v146
	v_mul_f32_e32 v163, 0xbfb8aa3b, v147
	v_mul_f32_e32 v164, 0xbfb8aa3b, v148
	v_mul_f32_e32 v165, 0xbfb8aa3b, v149
	v_mul_f32_e32 v166, 0xbfb8aa3b, v150
	v_mul_f32_e32 v167, 0xbfb8aa3b, v151
	v_mul_f32_e32 v168, 0xbfb8aa3b, v152
	v_mul_f32_e32 v169, 0xbfb8aa3b, v153
	v_exp_f32_e32 v162, v162
	v_exp_f32_e32 v163, v163
	v_exp_f32_e32 v164, v164
	v_exp_f32_e32 v165, v165
	v_exp_f32_e32 v166, v166
	v_exp_f32_e32 v167, v167
	v_exp_f32_e32 v168, v168
	v_exp_f32_e32 v169, v169
	v_add_f32_e32 v162, 1.0, v162
	v_add_f32_e32 v163, 1.0, v163
	v_add_f32_e32 v164, 1.0, v164
	v_add_f32_e32 v165, 1.0, v165
	v_add_f32_e32 v166, 1.0, v166
	v_add_f32_e32 v167, 1.0, v167
	v_add_f32_e32 v168, 1.0, v168
	v_add_f32_e32 v169, 1.0, v169
	v_rcp_f32_e32 v162, v162
	v_rcp_f32_e32 v163, v163
	v_rcp_f32_e32 v164, v164
	v_rcp_f32_e32 v165, v165
	v_rcp_f32_e32 v166, v166
	v_rcp_f32_e32 v167, v167
	v_rcp_f32_e32 v168, v168
	v_rcp_f32_e32 v169, v169
	s_nop 0
	v_pk_mul_f32 v[146:147], v[146:147], v[162:163]
	v_pk_mul_f32 v[148:149], v[148:149], v[164:165]
	v_pk_mul_f32 v[150:151], v[150:151], v[166:167]
	v_pk_mul_f32 v[152:153], v[152:153], v[168:169]
	v_pk_mul_f32 v[146:147], v[154:155], v[146:147]
	v_pk_mul_f32 v[148:149], v[156:157], v[148:149]
	v_pk_mul_f32 v[150:151], v[158:159], v[150:151]
	v_pk_mul_f32 v[152:153], v[160:161], v[152:153]
	v_cvt_pk_bf16_f32 v162, v146, v147
	v_cvt_pk_bf16_f32 v163, v148, v149
	v_cvt_pk_bf16_f32 v164, v150, v151
	v_cvt_pk_bf16_f32 v165, v152, v153
	global_store_dwordx4 v173, v[162:165], s[20:21]
	v_add_u32_e32 v173, 0x5600, v173
	s_waitcnt vmcnt(10)
	v_lshlrev_b32_e32 v98, 16, v90
	v_and_b32_e32 v99, 0xffff0000, v90
	v_lshlrev_b32_e32 v100, 16, v91
	v_and_b32_e32 v101, 0xffff0000, v91
	v_lshlrev_b32_e32 v102, 16, v92
	v_and_b32_e32 v103, 0xffff0000, v92
	v_lshlrev_b32_e32 v104, 16, v93
	v_and_b32_e32 v105, 0xffff0000, v93
	v_lshlrev_b32_e32 v106, 16, v94
	v_and_b32_e32 v107, 0xffff0000, v94
	v_lshlrev_b32_e32 v108, 16, v95
	v_and_b32_e32 v109, 0xffff0000, v95
	v_lshlrev_b32_e32 v110, 16, v96
	v_and_b32_e32 v111, 0xffff0000, v96
	v_lshlrev_b32_e32 v112, 16, v97
	v_and_b32_e32 v113, 0xffff0000, v97
	global_load_dwordx4 v[90:93], v180, s[16:17] nt
	global_load_dwordx4 v[94:97], v180, s[18:19] nt
	v_add_u32_e32 v180, s26, v180
	v_pk_fma_f32 v[146:147], v[2:3], v[114:115], v[50:51]
	v_pk_fma_f32 v[148:149], v[4:5], v[116:117], v[52:53]
	v_pk_fma_f32 v[150:151], v[6:7], v[118:119], v[54:55]
	v_pk_fma_f32 v[152:153], v[8:9], v[120:121], v[56:57]
	v_pk_fma_f32 v[154:155], v[26:27], v[122:123], v[58:59]
	v_pk_fma_f32 v[156:157], v[28:29], v[124:125], v[60:61]
	v_pk_fma_f32 v[158:159], v[30:31], v[126:127], v[62:63]
	v_pk_fma_f32 v[160:161], v[32:33], v[128:129], v[64:65]
	v_pk_fma_f32 v[146:147], v[10:11], v[130:131], v[146:147]
	v_pk_fma_f32 v[148:149], v[12:13], v[132:133], v[148:149]
	v_pk_fma_f32 v[150:151], v[14:15], v[134:135], v[150:151]
	v_pk_fma_f32 v[152:153], v[16:17], v[136:137], v[152:153]
	v_pk_fma_f32 v[154:155], v[34:35], v[138:139], v[154:155]
	v_pk_fma_f32 v[156:157], v[36:37], v[140:141], v[156:157]
	v_pk_fma_f32 v[158:159], v[38:39], v[142:143], v[158:159]
	v_pk_fma_f32 v[160:161], v[40:41], v[144:145], v[160:161]
	v_pk_fma_f32 v[146:147], v[18:19], v[98:99], v[146:147]
	v_pk_fma_f32 v[148:149], v[20:21], v[100:101], v[148:149]
	v_pk_fma_f32 v[150:151], v[22:23], v[102:103], v[150:151]
	v_pk_fma_f32 v[152:153], v[24:25], v[104:105], v[152:153]
	v_pk_fma_f32 v[154:155], v[42:43], v[106:107], v[154:155]
	v_pk_fma_f32 v[156:157], v[44:45], v[108:109], v[156:157]
	v_pk_fma_f32 v[158:159], v[46:47], v[110:111], v[158:159]
	v_pk_fma_f32 v[160:161], v[48:49], v[112:113], v[160:161]
	v_mul_f32_e32 v162, 0xbfb8aa3b, v146
	v_mul_f32_e32 v163, 0xbfb8aa3b, v147
	v_mul_f32_e32 v164, 0xbfb8aa3b, v148
	v_mul_f32_e32 v165, 0xbfb8aa3b, v149
	v_mul_f32_e32 v166, 0xbfb8aa3b, v150
	v_mul_f32_e32 v167, 0xbfb8aa3b, v151
	v_mul_f32_e32 v168, 0xbfb8aa3b, v152
	v_mul_f32_e32 v169, 0xbfb8aa3b, v153
	v_exp_f32_e32 v162, v162
	v_exp_f32_e32 v163, v163
	v_exp_f32_e32 v164, v164
	v_exp_f32_e32 v165, v165
	v_exp_f32_e32 v166, v166
	v_exp_f32_e32 v167, v167
	v_exp_f32_e32 v168, v168
	v_exp_f32_e32 v169, v169
	v_add_f32_e32 v162, 1.0, v162
	v_add_f32_e32 v163, 1.0, v163
	v_add_f32_e32 v164, 1.0, v164
	v_add_f32_e32 v165, 1.0, v165
	v_add_f32_e32 v166, 1.0, v166
	v_add_f32_e32 v167, 1.0, v167
	v_add_f32_e32 v168, 1.0, v168
	v_add_f32_e32 v169, 1.0, v169
	v_rcp_f32_e32 v162, v162
	v_rcp_f32_e32 v163, v163
	v_rcp_f32_e32 v164, v164
	v_rcp_f32_e32 v165, v165
	v_rcp_f32_e32 v166, v166
	v_rcp_f32_e32 v167, v167
	v_rcp_f32_e32 v168, v168
	v_rcp_f32_e32 v169, v169
	s_nop 0
	v_pk_mul_f32 v[146:147], v[146:147], v[162:163]
	v_pk_mul_f32 v[148:149], v[148:149], v[164:165]
	v_pk_mul_f32 v[150:151], v[150:151], v[166:167]
	v_pk_mul_f32 v[152:153], v[152:153], v[168:169]
	v_pk_mul_f32 v[146:147], v[154:155], v[146:147]
	v_pk_mul_f32 v[148:149], v[156:157], v[148:149]
	v_pk_mul_f32 v[150:151], v[158:159], v[150:151]
	v_pk_mul_f32 v[152:153], v[160:161], v[152:153]
	v_cvt_pk_bf16_f32 v162, v146, v147
	v_cvt_pk_bf16_f32 v163, v148, v149
	v_cvt_pk_bf16_f32 v164, v150, v151
	v_cvt_pk_bf16_f32 v165, v152, v153
	global_store_dwordx4 v173, v[162:165], s[20:21]
	v_add_u32_e32 v173, 0x5600, v173
	v_mov_b32_e32 v114, v98
	v_mov_b32_e32 v115, v99
	v_mov_b32_e32 v116, v100
	v_mov_b32_e32 v117, v101
	v_mov_b32_e32 v118, v102
	v_mov_b32_e32 v119, v103
	v_mov_b32_e32 v120, v104
	v_mov_b32_e32 v121, v105
	v_mov_b32_e32 v122, v106
	v_mov_b32_e32 v123, v107
	v_mov_b32_e32 v124, v108
	v_mov_b32_e32 v125, v109
	v_mov_b32_e32 v126, v110
	v_mov_b32_e32 v127, v111
	v_mov_b32_e32 v128, v112
	v_mov_b32_e32 v129, v113
	v_mov_b32_e32 v98, v130
	v_mov_b32_e32 v99, v131
	v_mov_b32_e32 v100, v132
	v_mov_b32_e32 v101, v133
	v_mov_b32_e32 v102, v134
	v_mov_b32_e32 v103, v135
	v_mov_b32_e32 v104, v136
	v_mov_b32_e32 v105, v137
	v_mov_b32_e32 v106, v138
	v_mov_b32_e32 v107, v139
	v_mov_b32_e32 v108, v140
	v_mov_b32_e32 v109, v141
	v_mov_b32_e32 v110, v142
	v_mov_b32_e32 v111, v143
	v_mov_b32_e32 v112, v144
	v_mov_b32_e32 v113, v145
	v_mov_b32_e32 v172, v180
	s_sub_u32 s22, s22, 1
	s_cmp_lg_u32 s22, 0
	s_cbranch_scc1 .Lgrp_cz0
	s_waitcnt vmcnt(0)
	v_lshrrev_b32_e32 v1, 6, v0
	v_lshlrev_b32_e32 v1, 14, v1
	v_and_b32_e32 v2, 63, v0
	v_lshl_or_b32 v1, v2, 4, v1
	ds_read_b128 v[138:141], v1
	ds_read_b128 v[142:145], v1 offset:1024
	ds_read_b128 v[146:149], v1 offset:2048
	ds_read_b128 v[150:153], v1 offset:3072
	ds_read_b128 v[154:157], v1 offset:4096
	ds_read_b128 v[158:161], v1 offset:5120
	ds_read_b128 v[162:165], v1 offset:6144
	ds_read_b128 v[166:169], v1 offset:7168
	ds_read_b128 v[170:173], v1 offset:8192
	ds_read_b128 v[174:177], v1 offset:9216
	ds_read_b128 v[178:181], v1 offset:10240
	ds_read_b128 v[182:185], v1 offset:11264
	ds_read_b128 v[186:189], v1 offset:12288
	ds_read_b128 v[190:193], v1 offset:13312
	ds_read_b128 v[194:197], v1 offset:14336
	ds_read_b128 v[198:201], v1 offset:15360
	s_waitcnt lgkmcnt(0)
